# norm1 row ownership permuted XCD-major (chunk = (bid&7)*32 + bid>>3) so the delta rows it reads were mostly written by the same XCD's out-projection tiles (L2-local)
# speedup vs baseline: 1.0122x; 1.0019x over previous
.LBB0_1128:
	s_or_b64 exec, exec, s[0:1]
	v_ashrrev_i32_e32 v0, 6, v16
	s_lshr_b32 s98, s90, 3
	s_and_b32 s99, s98, 7
	s_lshl_b32 s99, s99, 5
	s_lshr_b32 s98, s98, 3
	s_or_b32 s98, s98, s99
	s_lshl_b32 s98, s98, 3
	v_add_u32_e32 v0, s98, v0
	v_readlane_b32 s0, v254, 21
	s_movk_i32 s16, 0x3000
	s_nop 0
	v_mul_lo_u32 v128, s0, v0
	v_add_u32_e32 v0, s0, v128
	v_min_i32_e32 v226, 0x3000, v0
	v_cmp_lt_i32_e32 vcc, v128, v226
	s_and_saveexec_b64 s[0:1], vcc
	s_cbranch_execz .LBB0_1201
	v_lshlrev_b32_e32 v0, 2, v16
	v_and_b32_e32 v18, 0xfc, v0
	v_mov_b32_e32 v131, 0
	v_lshlrev_b32_e32 v130, 2, v18
	v_lshl_add_u64 v[0:1], s[50:51], 0, v[130:131]
	s_mov_b64 s[4:5], 0x1000
	v_add_co_u32_e32 v8, vcc, 0x1000, v0
	s_waitcnt vmcnt(3)
	v_lshl_add_u64 v[12:13], v[0:1], 0, s[4:5]
	v_addc_co_u32_e32 v9, vcc, 0, v1, vcc
	global_load_dwordx4 v[0:3], v[12:13], off offset:1024
	global_load_dwordx4 v[4:7], v[12:13], off offset:2048
	s_nop 0
	global_load_dwordx4 v[8:11], v[8:9], off
	s_nop 0
	global_load_dwordx4 v[12:15], v[12:13], off offset:3072
	v_mbcnt_hi_u32_b32 v17, -1, v225
	v_and_b32_e32 v19, 64, v17
	v_add_u32_e32 v19, 64, v19
	v_xor_b32_e32 v22, 32, v17
	v_cmp_lt_i32_e32 vcc, v22, v19
	s_add_u32 s4, s54, 0x3000
	s_addc_u32 s5, s55, 0
	v_cndmask_b32_e32 v22, v17, v22, vcc
	v_lshlrev_b32_e32 v228, 2, v22
	v_xor_b32_e32 v22, 16, v17
	v_cmp_lt_i32_e32 vcc, v22, v19
	v_lshlrev_b32_e32 v20, 1, v18
	v_mov_b32_e32 v21, v131
	v_cndmask_b32_e32 v22, v17, v22, vcc
	v_lshlrev_b32_e32 v229, 2, v22
	v_xor_b32_e32 v22, 8, v17
	v_cmp_lt_i32_e32 vcc, v22, v19
	s_add_u32 s6, s54, 0x4000
	v_lshl_add_u64 v[132:133], s[30:31], 0, v[20:21]
	v_cndmask_b32_e32 v22, v17, v22, vcc
	v_lshlrev_b32_e32 v230, 2, v22
	v_xor_b32_e32 v22, 4, v17
	v_cmp_lt_i32_e32 vcc, v22, v19
	v_lshl_add_u64 v[134:135], s[10:11], 0, v[20:21]
	s_addc_u32 s7, s55, 0
	v_cndmask_b32_e32 v22, v17, v22, vcc
	v_lshlrev_b32_e32 v231, 2, v22
	v_xor_b32_e32 v22, 2, v17
	v_cmp_lt_i32_e32 vcc, v22, v19
	v_or_b32_e32 v20, 0x400, v130
	v_lshl_add_u64 v[136:137], s[4:5], 0, v[130:131]
	v_cndmask_b32_e32 v22, v17, v22, vcc
	v_lshlrev_b32_e32 v232, 2, v22
	v_xor_b32_e32 v22, 1, v17
	v_cmp_lt_i32_e32 vcc, v22, v19
	v_lshl_add_u64 v[138:139], s[6:7], 0, v[130:131]
	v_lshl_add_u64 v[140:141], s[4:5], 0, v[20:21]
	v_lshl_add_u64 v[142:143], s[6:7], 0, v[20:21]
	v_or_b32_e32 v20, 0x800, v130
	v_or_b32_e32 v130, 0xc00, v130
	v_and_b32_e32 v16, 63, v16
	v_cndmask_b32_e32 v17, v17, v22, vcc
	v_lshl_add_u64 v[148:149], s[4:5], 0, v[130:131]
	v_lshl_add_u64 v[150:151], s[6:7], 0, v[130:131]
	v_lshlrev_b32_e32 v130, 4, v16
	v_mov_b32_e32 v72, v131
	v_mov_b32_e32 v73, v131
	v_mov_b32_e32 v74, v131
	v_mov_b32_e32 v75, v131
	v_lshlrev_b32_e32 v233, 2, v17
	v_lshl_add_u64 v[144:145], s[4:5], 0, v[20:21]
	v_lshl_add_u64 v[146:147], s[6:7], 0, v[20:21]
	v_lshl_add_u64 v[152:153], s[24:25], 0, v[130:131]
	v_lshlrev_b32_e32 v130, 2, v18
	v_mov_b64_e32 v[48:49], v[72:73]
	s_waitcnt vmcnt(6)
	v_mov_b64_e32 v[24:25], v[72:73]
	v_mov_b64_e32 v[16:17], v[72:73]
	v_mov_b64_e32 v[20:21], v[72:73]
	v_mov_b64_e32 v[28:29], v[72:73]
	v_mov_b64_e32 v[52:53], v[72:73]
	v_mov_b64_e32 v[78:79], v[74:75]
	v_mov_b32_e32 v235, -1
	v_add_u32_e32 v227, -1, v226
	s_mov_b64 s[4:5], 0
	s_movk_i32 s17, 0x2000
	s_movk_i32 s19, 0x1fff
	v_mov_b32_e32 v234, 0x358637bd
	s_mov_b32 s28, 0x800000
	s_movk_i32 s29, 0x1ffe
	s_movk_i32 s46, 0x1ffd
	s_movk_i32 s47, 0x1ffc
	s_movk_i32 s48, 0x1ffb
	s_movk_i32 s49, 0x1ffa
	v_mov_b64_e32 v[50:51], v[74:75]
	v_mov_b64_e32 v[26:27], v[74:75]
	v_mov_b64_e32 v[18:19], v[74:75]
	v_mov_b64_e32 v[22:23], v[74:75]
	v_mov_b64_e32 v[30:31], v[74:75]
	v_mov_b64_e32 v[54:55], v[74:75]
	v_mov_b64_e32 v[76:77], v[72:73]
	s_branch .LBB0_1132
